# attention tile rewritten on 16x16x32 bf16 MFMA: new Q/K/V fragment layouts (V staging image and transposed reads re-addressed), packed P without cross-lane swaps, per-query-block row sums, epilogues r
# speedup vs baseline: 1.0247x; 1.0063x over previous
; __device__ __forceinline__ float shx(float v, int o, int lane) { return __int_as_float(__builtin_amdgcn_ds_bpermute((lane ^ o) << 2, __float_as_int(v))); }
; __device__ __forceinline__ int v_rd_base(int lane) { return ((lane & 3) << 3) | (((lane >> 2) & 3) << 6) | (((lane >> 4) & 1) << 5) | (((lane >> 5) & 1) << 8); }
; __device__ __forceinline__ void attn_unit(const bf16_t* __restrict__ Qb, const bf16_t* __restrict__ Kh, const bf16_t* __restrict__ Vh, bf16_t* __restrict__ Ob,
;                                           LAS unsigned char* lds, float MB, int tid, int nrows, int t0, int t1, float* part, float* partl) {
;     ...
;     unsigned ko[3], vo[2];
; #pragma unroll
;     for (int i = 0; i < 3; ++i) { const int sl = tid + 512 * i, row = sl / 24, pc = sl - row * 24, ch = pc ^ ((row >> 1) & 7); ko[i] = (unsigned)(row * LDKK + ch * 8) * 2u; }
; #pragma unroll
;     for (int i = 0; i < 2; ++i) { const int sl = tid + 512 * i, sub = sl >> 5, kk = (sub >> 2) * 8 + ((sl >> 2) & 7), c = (sub & 3) * 32 + (sl & 3) * 8;
;         const int kx = (kk & ~0xC) | ((kk & 4) << 1) | ((kk & 8) >> 1); vo[i] = (unsigned)(kx * LDV + c) * 2u; }
;     const int vb0 = (int)(unsigned)(uintptr_t)V_lds + v_rd_base(lane);
;     const unsigned ldw = (unsigned)wid * 1024u;
; __global__ void __launch_bounds__(512, 2) mk_fwd(Args a) {
;     ...
;                 const float* gq = a.in[I_GQ] + (size_t)l * 192; const float* gk = a.in[I_GK] + (size_t)l * 192;
;                 float mq = fmaxf(fmaxf(fabsf(gq[lane]), fabsf(gq[64 + lane])), fabsf(gq[128 + lane])), mk = fmaxf(fmaxf(fabsf(gk[lane]), fabsf(gk[64 + lane])), fabsf(gk[128 + lane]));
; #pragma unroll
;                 for (int o = 1; o < 64; o <<= 1) { mq = fmaxf(mq, shx(mq, o, lane)); mk = fmaxf(mk, shx(mk, o, lane)); }
;                 const float bound = mq * mk * 13.856406460551018f * 1.4426950408889634f;
;                 const float MBs = fmaxf(0.f, bound - 60.f);
.LBB0_124:
	s_and_b64 vcc, exec, s[0:1]
	s_cbranch_vccz .LBB0_227
	v_ashrrev_i32_e32 v151, 31, v150
	v_lshlrev_b64 v[0:1], 2, v[150:151]
	s_waitcnt lgkmcnt(0)
	v_lshl_add_u64 v[2:3], s[44:45], 0, v[0:1]
	global_load_dword v4, v[2:3], off
	global_load_dword v5, v[2:3], off offset:256
	s_nop 0
	global_load_dword v2, v[2:3], off offset:512
	v_lshl_add_u64 v[0:1], s[14:15], 0, v[0:1]
	v_readlane_b32 s0, v252, 52
	v_and_b32_e32 v151, 31, v150
	v_readlane_b32 s1, v252, 53
	v_lshlrev_b32_e32 v205, 3, v150
	s_andn2_b64 vcc, exec, s[0:1]
	v_lshlrev_b32_e32 v154, 2, v151
	s_waitcnt vmcnt(0)
	v_max3_f32 v2, |v4|, |v5|, |v2|
	global_load_dword v3, v[0:1], off
	global_load_dword v4, v[0:1], off offset:256
	s_nop 0
	global_load_dword v0, v[0:1], off offset:512
	s_waitcnt vmcnt(0)
	v_max3_f32 v0, |v3|, |v4|, |v0|
	v_lshlrev_b32_e32 v3, 2, v150
	v_xor_b32_e32 v1, 4, v3
	ds_bpermute_b32 v4, v1, v2
	ds_bpermute_b32 v1, v1, v0
	s_waitcnt lgkmcnt(0)
	v_max_f32_e32 v4, v4, v4
	v_max_f32_e32 v1, v1, v1
	v_max_f32_e32 v2, v2, v4
	v_max_f32_e32 v0, v0, v1
	v_xor_b32_e32 v1, 8, v3
	ds_bpermute_b32 v4, v1, v2
	ds_bpermute_b32 v1, v1, v0
	s_waitcnt lgkmcnt(1)
	v_max_f32_e32 v4, v4, v4
	s_waitcnt lgkmcnt(0)
	v_max_f32_e32 v1, v1, v1
	v_max_f32_e32 v2, v2, v4
	v_max_f32_e32 v0, v0, v1
	v_xor_b32_e32 v1, 16, v3
	ds_bpermute_b32 v4, v1, v2
	ds_bpermute_b32 v1, v1, v0
	s_waitcnt lgkmcnt(1)
	v_max_f32_e32 v4, v4, v4
	s_waitcnt lgkmcnt(0)
	v_max_f32_e32 v1, v1, v1
	v_max_f32_e32 v2, v2, v4
	v_max_f32_e32 v0, v0, v1
	v_xor_b32_e32 v1, 32, v3
	ds_bpermute_b32 v4, v1, v2
	ds_bpermute_b32 v1, v1, v0
	s_waitcnt lgkmcnt(1)
	v_max_f32_e32 v4, v4, v4
	v_max_f32_e32 v2, v2, v4
	s_waitcnt lgkmcnt(0)
	v_max_f32_e32 v1, v1, v1
	v_xor_b32_e32 v4, 64, v3
	v_max_f32_e32 v1, v0, v1
	ds_bpermute_b32 v0, v4, v2
	s_waitcnt lgkmcnt(0)
	v_max_f32_e32 v0, v0, v0
	v_max_f32_e32 v0, v2, v0
	ds_bpermute_b32 v2, v4, v1
	s_waitcnt lgkmcnt(0)
	v_max_f32_e32 v2, v2, v2
	v_max_f32_e32 v1, v1, v2
	v_xor_b32_e32 v2, 0x80, v3
	ds_bpermute_b32 v3, v2, v0
	ds_bpermute_b32 v2, v2, v1
	s_cbranch_vccnz .LBB0_182
	s_waitcnt lgkmcnt(1)
	v_max_f32_e32 v3, v3, v3
	v_max_f32_e32 v0, v0, v0
	s_waitcnt lgkmcnt(0)
	v_max_f32_e32 v2, v2, v2
	v_max_f32_e32 v1, v1, v1
	v_max_f32_e32 v0, v0, v3
	v_max_f32_e32 v1, v1, v2
	v_mul_f32_e32 v0, v1, v0
	v_mul_f32_e32 v0, 0x415db3d7, v0
	v_fmamk_f32 v0, v0, 0x3fb8aa3b, v249
	s_mov_b32 s5, 0x2aaaaaab
	v_max_f32_e32 v206, 0, v0
	v_mul_hi_i32 v0, v152, s5
	v_lshrrev_b32_e32 v1, 31, v0
	v_ashrrev_i32_e32 v0, 2, v0
	v_add_u32_e32 v2, v0, v1
	s_mov_b32 s8, 0xfffffe8
	v_mad_u64_u32 v[0:1], s[0:1], v2, s8, v[152:153]
	v_lshrrev_b32_e32 v1, 1, v2
	s_movk_i32 s4, 0x1800
	v_bitop3_b32 v0, v0, v1, 7 bitop3:0x78
	v_mul_lo_u32 v1, v2, s4
	v_lshl_add_u32 v156, v0, 4, v1
	v_add_u32_e32 v0, 0x200, v152
	v_mul_hi_i32 v1, v0, s5
	v_lshrrev_b32_e32 v2, 31, v1
	v_ashrrev_i32_e32 v1, 2, v1
	v_add_u32_e32 v1, v1, v2
	v_mad_u64_u32 v[2:3], s[0:1], v1, s8, v[0:1]
	v_lshrrev_b32_e32 v3, 1, v1
	v_bitop3_b32 v2, v2, v3, 7 bitop3:0x78
	v_mul_lo_u32 v1, v1, s4
	v_lshl_add_u32 v158, v2, 4, v1
	v_add_u32_e32 v2, 0x400, v152
	v_mul_hi_i32 v1, v2, s5
	v_lshrrev_b32_e32 v3, 31, v1
	v_ashrrev_i32_e32 v1, 2, v1
	v_add_u32_e32 v1, v1, v3
	v_mad_u64_u32 v[2:3], s[0:1], v1, s8, v[2:3]
	v_lshrrev_b32_e32 v3, 1, v1
	v_bitop3_b32 v2, v2, v3, 7 bitop3:0x78
	v_mul_lo_u32 v1, v1, s4
	v_lshl_add_u32 v160, v2, 4, v1
	v_bfe_u32 v1, v152, 2, 2
	v_lshrrev_b32_e32 v3, 1, v152
	v_and_or_b32 v1, v3, 8, v1
	v_ashrrev_i32_e32 v3, 4, v152
	v_and_b32_e32 v2, 0x60, v152
	v_and_b32_e32 v6, 0x7fff0, v3
	v_lshrrev_b32_e32 v3, 1, v3
	v_and_or_b32 v2, v205, 24, v2
	v_and_b32_e32 v3, 4, v3
	v_lshlrev_b32_e32 v2, 1, v2
	v_or3_b32 v3, v6, v3, v1
	v_ashrrev_i32_e32 v0, 4, v0
	v_lshl_or_b32 v162, v3, 13, v2
	v_and_b32_e32 v3, 0x7fff0, v0
	v_lshrrev_b32_e32 v0, 1, v0
	v_bfe_u32 v5, v150, 5, 1
	v_and_b32_e32 v0, 4, v0
	s_movk_i32 s0, 0x180
	v_lshlrev_b32_e32 v207, 4, v5
	v_or3_b32 v0, v3, v0, v1
	v_lshlrev_b32_e32 v3, 3, v151
	v_mad_u32_u24 v208, v151, s0, 0
	s_movk_i32 s0, 0x70
	v_and_b32_e32 v6, 0x70, v3
	v_bitop3_b32 v209, v207, v3, s0 bitop3:0x78
	s_movk_i32 s0, 0x60
	v_bitop3_b32 v212, v207, v6, s0 bitop3:0x36
	s_movk_i32 s0, 0x80
	v_bitop3_b32 v213, v207, v6, s0 bitop3:0x36
	s_movk_i32 s0, 0xa0
	v_bitop3_b32 v214, v207, v6, s0 bitop3:0x36
	s_movk_i32 s0, 0xc0
	v_bitop3_b32 v215, v207, v6, s0 bitop3:0x36
	s_movk_i32 s0, 0xe0
	v_bitop3_b32 v216, v207, v6, s0 bitop3:0x36
	s_movk_i32 s0, 0x100
	v_lshl_or_b32 v164, v0, 13, v2
	v_lshlrev_b32_e32 v0, 1, v150
	v_lshlrev_b32_e32 v1, 4, v150
	v_and_b32_e32 v2, 0x118, v205
	v_bitop3_b32 v217, v207, v6, s0 bitop3:0x36
	s_movk_i32 s0, 0x120
	v_and_b32_e32 v4, 63, v150
	v_and_b32_e32 v1, 0xc0, v1
	v_bitop3_b32 v218, v207, v6, s0 bitop3:0x36
	s_movk_i32 s0, 0x140
	v_and_or_b32 v0, v0, 32, v2
	s_add_u32 s6, s64, 0x2c7c1000
	v_bitop3_b32 v219, v207, v6, s0 bitop3:0x36
; __device__ __forceinline__ float shx(float v, int o, int lane) { return __int_as_float(__builtin_amdgcn_ds_bpermute((lane ^ o) << 2, __float_as_int(v))); }
; __device__ __forceinline__ int crow(int r, int hi) { return (r & 3) + 8 * (r >> 2) + 4 * hi; }
; __device__ __forceinline__ int v_rd_base(int lane) { return ((lane & 3) << 3) | (((lane >> 2) & 3) << 6) | (((lane >> 4) & 1) << 5) | (((lane >> 5) & 1) << 8); }
; __device__ __forceinline__ void attn_unit(const bf16_t* __restrict__ Qb, const bf16_t* __restrict__ Kh, const bf16_t* __restrict__ Vh, bf16_t* __restrict__ Ob,
;                                           LAS unsigned char* lds, float MB, int tid, int nrows, int t0, int t1, float* part, float* partl) {
;     ...
;     unsigned ko[3], vo[2];
; #pragma unroll
;     for (int i = 0; i < 3; ++i) { const int sl = tid + 512 * i, row = sl / 24, pc = sl - row * 24, ch = pc ^ ((row >> 1) & 7); ko[i] = (unsigned)(row * LDKK + ch * 8) * 2u; }
; #pragma unroll
;     for (int i = 0; i < 2; ++i) { const int sl = tid + 512 * i, sub = sl >> 5, kk = (sub >> 2) * 8 + ((sl >> 2) & 7), c = (sub & 3) * 32 + (sl & 3) * 8;
;         const int kx = (kk & ~0xC) | ((kk & 4) << 1) | ((kk & 8) >> 1); vo[i] = (unsigned)(kx * LDV + c) * 2u; }
;     const int vb0 = (int)(unsigned)(uintptr_t)V_lds + v_rd_base(lane);
;     const unsigned ldw = (unsigned)wid * 1024u;
;     ...
;     if (act && part) {
;         l_reg += shx(l_reg, 32, lane);
;         if (hi == 0 && r32 < 16) partl[r32] = l_reg;
; #pragma unroll
;         for (int r = 0; r < 8; ++r) {
; #pragma unroll
;             for (int d0 = 0; d0 < 4; ++d0) part[crow(r, hi) * 128 + d0 * 32 + r32] = o[d0][r]; }
	s_movk_i32 s0, 0x160
	v_add3_u32 v221, v1, 0, v0
	v_lshlrev_b32_e32 v0, 2, v4
	v_cmp_gt_u32_e64 s[38:39], 32, v4
	v_cmp_gt_u32_e32 vcc, 16, v151
	v_mov_b32_e32 v155, v145
	s_addc_u32 s7, s65, 0
	v_bitop3_b32 v220, v207, v6, s0 bitop3:0x36
	v_xor_b32_e32 v222, 0x80, v0
	v_lshlrev_b32_e32 v223, 2, v5
	s_and_b64 s[0:1], s[38:39], vcc
	v_lshl_add_u64 v[0:1], s[64:65], 0, v[154:155]
	s_mov_b64 s[8:9], 0x2c9c1000
	v_or_b32_e32 v239, 1, v223
	v_or_b32_e32 v250, 2, v223
	v_or_b32_e32 v203, 3, v223
	v_or_b32_e32 v248, 8, v223
	v_or_b32_e32 v228, 9, v223
	v_or_b32_e32 v229, 10, v223
	v_or_b32_e32 v230, 11, v223
	v_or_b32_e32 v231, 16, v223
	v_or_b32_e32 v232, 17, v223
	v_or_b32_e32 v233, 18, v223
	v_or_b32_e32 v234, 19, v223
	v_or_b32_e32 v235, 24, v223
	v_or_b32_e32 v236, 25, v223
	v_or_b32_e32 v237, 26, v223
	v_or_b32_e32 v238, 27, v223
	v_lshl_add_u64 v[198:199], v[0:1], 0, s[8:9]
	s_add_u32 s13, s64, 0x1fbc1000
	v_readlane_b32 s4, v252, 51
	v_readlane_b32 s8, v252, 47
	s_movk_i32 s5, 0x1800
	v_mov_b32_e32 v157, v145
	v_mov_b32_e32 v159, v145
	v_mov_b32_e32 v161, v145
	v_mov_b32_e32 v163, v145
	v_mov_b32_e32 v165, v145
	v_bitop3_b32 v210, v207, v6, 32 bitop3:0x36
	v_bitop3_b32 v211, v207, v6, 64 bitop3:0x36
	v_lshlrev_b32_e32 v166, 14, v5
	v_mov_b32_e32 v167, v145
	v_lshlrev_b32_e32 v168, 12, v239
	v_mov_b32_e32 v169, v145
	v_lshlrev_b32_e32 v170, 12, v250
	v_mov_b32_e32 v171, v145
	v_lshlrev_b32_e32 v172, 12, v203
	v_mov_b32_e32 v173, v145
	v_lshlrev_b32_e32 v174, 12, v248
	v_mov_b32_e32 v175, v145
	v_lshlrev_b32_e32 v176, 12, v228
	v_mov_b32_e32 v177, v145
	v_lshlrev_b32_e32 v178, 12, v229
	v_mov_b32_e32 v179, v145
	v_lshlrev_b32_e32 v180, 12, v230
	v_mov_b32_e32 v181, v145
	v_lshlrev_b32_e32 v182, 12, v231
	v_mov_b32_e32 v183, v145
	v_lshlrev_b32_e32 v184, 12, v232
	v_mov_b32_e32 v185, v145
	v_lshlrev_b32_e32 v186, 12, v233
	v_mov_b32_e32 v187, v145
	v_lshlrev_b32_e32 v188, 12, v234
	v_mov_b32_e32 v189, v145
	v_lshlrev_b32_e32 v190, 12, v235
	v_mov_b32_e32 v191, v145
	v_lshlrev_b32_e32 v192, 12, v236
	v_mov_b32_e32 v193, v145
	v_lshlrev_b32_e32 v194, 12, v237
	v_mov_b32_e32 v195, v145
	v_lshlrev_b32_e32 v196, 12, v238
	v_mov_b32_e32 v197, v145
	v_lshl_or_b32 v200, v5, 9, v151
	v_mov_b32_e32 v201, v145
	s_addc_u32 s18, s65, 0
	s_mov_b32 s24, 0
	s_mov_b32 s36, s4
	v_readlane_b32 s9, v252, 48
	v_and_b32_e32 v64, 15, v150
	v_bfe_u32 v65, v150, 4, 2
	v_lshrrev_b32_e32 v66, 1, v64
	v_xor_b32_e32 v67, v65, v66
	v_mul_u32_u24_e32 v68, 0x180, v64
	v_lshl_add_u32 v209, v67, 4, v68
	v_xor_b32_e32 v67, 4, v67
	v_lshl_add_u32 v210, v67, 4, v68
	v_lshrrev_b32_e32 v66, 1, v65
	v_and_b32_e32 v67, 1, v65
	v_lshlrev_b32_e32 v66, 11, v66
	v_lshl_or_b32 v66, v67, 7, v66
	v_lshrrev_b32_e32 v67, 2, v64
	v_lshl_or_b32 v66, v67, 5, v66
	v_and_b32_e32 v67, 3, v64
	v_lshl_or_b32 v221, v67, 3, v66
	v_lshl_or_b32 v200, v65, 9, v64
	v_lshrrev_b32_e32 v66, 7, v152
	v_bfe_u32 v67, v152, 1, 3
	v_lshl_or_b32 v66, v66, 3, v67
	v_bfe_u32 v67, v152, 4, 3
	v_and_b32_e32 v68, 1, v152
	v_lshl_or_b32 v67, v67, 1, v68
	v_lshlrev_b32_e32 v67, 4, v67
	v_lshl_or_b32 v162, v66, 13, v67
	v_add_u32_e32 v164, 0x40000, v162
	s_branch .LBB0_129
.LBB0_127:
	s_or_b64 exec, exec, s[48:49]
	s_lshl_b64 s[28:29], s[36:37], 13
	s_add_u32 s26, s6, s28
	s_addc_u32 s28, s7, s29
	s_and_b64 s[8:9], s[8:9], exec
	s_cselect_b32 s8, s28, 0
	s_cselect_b32 s9, s26, 0
	s_waitcnt lgkmcnt(0)
	v_mov_b32_e32 v40, s9
	v_mov_b32_e32 v41, s8
	v_lshl_add_u64 v[40:41], v[200:201], 2, v[40:41]
	s_movk_i32 s8, 0x1000
	flat_store_dword v[40:41], v0
	flat_store_dword v[40:41], v1 offset:512
	flat_store_dword v[40:41], v2 offset:1024
	flat_store_dword v[40:41], v3 offset:1536
	flat_store_dword v[40:41], v4 offset:64
	flat_store_dword v[40:41], v5 offset:576
	flat_store_dword v[40:41], v6 offset:1088
	flat_store_dword v[40:41], v7 offset:1600
	flat_store_dword v[40:41], v8 offset:128
	flat_store_dword v[40:41], v9 offset:640
	flat_store_dword v[40:41], v10 offset:1152
	flat_store_dword v[40:41], v11 offset:1664
	flat_store_dword v[40:41], v12 offset:192
	flat_store_dword v[40:41], v13 offset:704
	flat_store_dword v[40:41], v14 offset:1216
	flat_store_dword v[40:41], v15 offset:1728
	flat_store_dword v[40:41], v16 offset:256
	flat_store_dword v[40:41], v17 offset:768
	flat_store_dword v[40:41], v18 offset:1280
	flat_store_dword v[40:41], v19 offset:1792
	flat_store_dword v[40:41], v20 offset:320
	flat_store_dword v[40:41], v21 offset:832
	flat_store_dword v[40:41], v22 offset:1344
	flat_store_dword v[40:41], v23 offset:1856
	flat_store_dword v[40:41], v24 offset:384
	flat_store_dword v[40:41], v25 offset:896
	flat_store_dword v[40:41], v26 offset:1408
	flat_store_dword v[40:41], v27 offset:1920
	flat_store_dword v[40:41], v28 offset:448
	flat_store_dword v[40:41], v29 offset:960
	flat_store_dword v[40:41], v30 offset:1472
	flat_store_dword v[40:41], v31 offset:1984

; #define LAS __attribute__((address_space(3)))
; __device__ __forceinline__ void attn_unit(const bf16_t* __restrict__ Qb, const bf16_t* __restrict__ Kh, const bf16_t* __restrict__ Vh, bf16_t* __restrict__ Ob,
;                                           LAS unsigned char* lds, float MB, int tid, int nrows, int t0, int t1, float* part, float* partl) {
;     const int wid = __builtin_amdgcn_readfirstlane(tid >> 6), lane = tid & 63, r32 = lane & 31, hi = lane >> 5;
;     LAS unsigned char* V_lds = lds + LDS_V; LAS unsigned char* K_lds = lds + LDS_K;
;     LAS float* li_l = (LAS float*)(lds + LDS_WS) + wid * 64;
;     const bool act = wid * 32 < nrows;
;     float l_reg = 0.f; f32x16 o[4] = {}; bf16x8 qr[QREG];
;     LAS unsigned char* qt = lds + LDS_QT + wid * ((12 - QREG) * 1024) + lane * 16;
;     const unsigned qo = (unsigned)((wid * 32 + r32) * LDQ + hi * 8) * 2u;
; #pragma unroll
;     for (int d0 = 0; d0 < QREG; ++d0) qr[d0] = *(const bf16x8*)((const char*)Qb + qo + d0 * 32);
; #pragma unroll
;     for (int d0 = QREG; d0 < 12; ++d0) *(LAS bf16x8*)(qt + (d0 - QREG) * 1024) = *(const bf16x8*)((const char*)Qb + qo + d0 * 32);
;     unsigned ko[3], vo[2];
; #pragma unroll
;     for (int i = 0; i < 3; ++i) { const int sl = tid + 512 * i, row = sl / 24, pc = sl - row * 24, ch = pc ^ ((row >> 1) & 7); ko[i] = (unsigned)(row * LDKK + ch * 8) * 2u; }
; #pragma unroll
;     for (int i = 0; i < 2; ++i) { const int sl = tid + 512 * i, sub = sl >> 5, kk = (sub >> 2) * 8 + ((sl >> 2) & 7), c = (sub & 3) * 32 + (sl & 3) * 8;
; __global__ void __launch_bounds__(512, 2) mk_fwd(Args a) {
;     ...
;                 for (int it = 0;; ++it) { const bool mt = it >= nr; const int mp = mp0 + (it - nr) * mstep;
;                     if (mt && (mp < 0 || mp >= 16 * NMP)) break;
;                     const int un = bx + it * G;
;                     const int h = mt ? mp / NMP : (un & 7) | ((un >> 8) << 3), qrow = mt ? LREAL : ((un >> 3) & 31) * 256, pc = mt ? mp - h * NMP : 0;
;                     const int t0 = mt ? (pc * att::NT) / NMP : 0, t1 = mt ? ((pc + 1) * att::NT) / NMP : att::NT;
;                     att::attn_unit(Q + (size_t)qrow * NQ + h * 192, KP + h * 192, KV + h * 256 + 128, AO + (size_t)qrow * DM + h * 128, lds, MBs, tid, mt ? 16 : 256, t0, t1,
;                                    mt ? PM + (size_t)mp * 16 * 128 : nullptr, mt ? PM + PM_L + (size_t)mp * 16 : nullptr); }
.LBB0_133:
	s_lshl_b32 s28, s28, 5
	s_and_b32 s28, s28, 0x1f00
	s_and_b64 s[46:47], s[8:9], exec
	s_cselect_b32 s48, 0x2000, s28
	s_mul_i32 s28, s29, -7
	s_cselect_b32 s49, 0, 0
	s_add_i32 s28, s28, s36
	s_mulk_i32 s28, 0x81
	s_and_b64 s[46:47], s[8:9], exec
	s_cselect_b32 s28, s28, 0
	s_mul_hi_i32 s33, s28, 0x92492493
	s_add_i32 s33, s33, s28
	s_lshr_b32 s37, s33, 31
	s_ashr_i32 s33, s33, 2
	s_add_i32 s33, s33, s37
	s_and_b64 s[46:47], s[8:9], exec
	s_cselect_b32 s46, s33, 0
	s_addk_i32 s28, 0x81
	s_mul_hi_i32 s33, s28, 0x92492493
	s_add_i32 s33, s33, s28
	s_lshr_b32 s28, s33, 31
	s_ashr_i32 s33, s33, 2
	s_add_i32 s33, s33, s28
	s_and_b64 s[50:51], s[8:9], exec
	s_mul_i32 s28, s48, 0x1800
	s_cselect_b32 s47, s33, 0x81
	s_add_u32 s28, s84, s28
	s_mul_i32 s50, s29, 0xc0
	s_addc_u32 s33, s85, 0
	s_ashr_i32 s51, s50, 31
	s_lshl_b64 s[50:51], s[50:51], 1
	s_add_u32 s52, s28, s50
	s_addc_u32 s53, s33, s51
	s_add_u32 s54, s13, s50
	s_addc_u32 s55, s18, s51
	s_lshl_b32 s50, s29, 8
	s_ashr_i32 s51, s50, 31
	s_lshl_b64 s[50:51], s[50:51], 1
	v_readlane_b32 s42, v254, 40
	v_readlane_b32 s43, v254, 41
	s_add_u32 s56, s42, s50
	v_readfirstlane_b32 s37, v152
	s_addc_u32 s57, s43, s51
	s_ashr_i32 s33, s37, 6
	s_lshl_b32 s28, s33, 5
	v_and_b32_e32 v0, 15, v150
	v_or_b32_e32 v0, s28, v0
	v_mul_lo_u32 v0, v0, s5
	v_and_b32_e32 v144, 0x30, v150
	v_or_b32_e32 v144, v0, v144
	s_cmp_lt_i32 s28, s26
	v_lshl_add_u64 v[0:1], s[52:53], 0, v[144:145]
	s_cselect_b64 s[50:51], -1, 0
	s_lshl_b32 s52, s46, 6
	s_ashr_i32 s53, s52, 31
	s_lshl_b32 s42, s33, 10
	s_lshl_b64 s[62:63], s[52:53], 13
	s_mul_i32 s43, s46, 0x60000
	v_add_co_u32_e32 v2, vcc, 0x18000, v0
	s_nop 1
	v_addc_co_u32_e32 v3, vcc, 0, v1, vcc
	flat_load_dwordx4 v[96:99], v[0:1]
	flat_load_dwordx4 v[100:103], v[0:1] offset:64
	flat_load_dwordx4 v[104:107], v[0:1] offset:128
	flat_load_dwordx4 v[108:111], v[0:1] offset:192
	flat_load_dwordx4 v[112:115], v[0:1] offset:256
	flat_load_dwordx4 v[116:119], v[0:1] offset:320
	flat_load_dwordx4 v[120:123], v[2:3]
	flat_load_dwordx4 v[124:127], v[2:3] offset:64
	flat_load_dwordx4 v[128:131], v[2:3] offset:128
	flat_load_dwordx4 v[132:135], v[2:3] offset:192
	flat_load_dwordx4 v[136:139], v[2:3] offset:256
	flat_load_dwordx4 v[140:143], v[2:3] offset:320
	s_mul_hi_i32 s53, s52, 0x1800
	s_add_u32 s60, s54, s43
	s_addc_u32 s61, s55, s53
	s_add_i32 s58, s42, 0
	s_add_i32 m0, s58, 0x8000
	v_lshl_add_u64 v[0:1], s[60:61], 0, v[156:157]
	s_add_i32 s59, s58, 0xa000
	global_load_lds_dwordx4 v[0:1], off
	v_lshl_add_u64 v[0:1], s[60:61], 0, v[158:159]
	s_mov_b32 m0, s59
	v_mov_b32_e32 v15, 0
	global_load_lds_dwordx4 v[0:1], off
	v_lshl_add_u64 v[0:1], s[60:61], 0, v[160:161]
	s_add_i32 s60, s58, 0xc000
	s_add_u32 s62, s56, s62
	s_mov_b32 m0, s60
	s_addc_u32 s63, s57, s63
	global_load_lds_dwordx4 v[0:1], off
	v_lshl_add_u64 v[0:1], s[62:63], 0, v[162:163]
	v_lshl_add_u64 v[0:1], v[0:1], 0, s[20:21]
	s_mov_b32 m0, s58
	v_mov_b32_e32 v14, v15
	global_load_lds_dwordx4 v[0:1], off
	v_lshl_add_u64 v[0:1], s[62:63], 0, v[164:165]
	v_lshl_add_u64 v[0:1], v[0:1], 0, s[20:21]
	s_add_i32 m0, s58, 0x2000
	s_cmp_ge_i32 s46, s47
	global_load_lds_dwordx4 v[0:1], off
	s_waitcnt vmcnt(0)
	v_mov_b32_e32 v13, v15
	v_mov_b32_e32 v12, v15
	v_mov_b32_e32 v11, v15
	v_mov_b32_e32 v10, v15
	v_mov_b32_e32 v9, v15
	v_mov_b32_e32 v8, v15
	v_mov_b32_e32 v7, v15
	v_mov_b32_e32 v6, v15
	v_mov_b32_e32 v5, v15
	v_mov_b32_e32 v4, v15
	v_mov_b32_e32 v3, v15
	v_mov_b32_e32 v2, v15
	v_mov_b32_e32 v1, v15
	v_mov_b32_e32 v0, v15
	v_mov_b32_e32 v31, v15
	v_mov_b32_e32 v30, v15
	v_mov_b32_e32 v29, v15
	v_mov_b32_e32 v28, v15
	v_mov_b32_e32 v27, v15
	v_mov_b32_e32 v26, v15
	v_mov_b32_e32 v25, v15
	v_mov_b32_e32 v24, v15
	v_mov_b32_e32 v23, v15
	v_mov_b32_e32 v22, v15
	v_mov_b32_e32 v21, v15
	v_mov_b32_e32 v20, v15
	v_mov_b32_e32 v19, v15
	v_mov_b32_e32 v18, v15
	v_mov_b32_e32 v17, v15
	v_mov_b32_e32 v16, v15
	v_mov_b32_e32 v47, v15
	v_mov_b32_e32 v46, v15
	v_mov_b32_e32 v45, v15
	v_mov_b32_e32 v44, v15
	v_mov_b32_e32 v43, v15
	v_mov_b32_e32 v42, v15
	v_mov_b32_e32 v41, v15
	v_mov_b32_e32 v40, v15
	v_mov_b32_e32 v39, v15
	v_mov_b32_e32 v38, v15
	v_mov_b32_e32 v37, v15
	v_mov_b32_e32 v36, v15
	v_mov_b32_e32 v35, v15
	v_mov_b32_e32 v34, v15
	v_mov_b32_e32 v33, v15
	v_mov_b32_e32 v32, v15
	v_mov_b32_e32 v63, v15
	v_mov_b32_e32 v62, v15
	v_mov_b32_e32 v61, v15
	v_mov_b32_e32 v60, v15
	v_mov_b32_e32 v59, v15
	v_mov_b32_e32 v58, v15
	v_mov_b32_e32 v57, v15
	v_mov_b32_e32 v56, v15
	v_mov_b32_e32 v55, v15
	v_mov_b32_e32 v54, v15
	v_mov_b32_e32 v53, v15
	v_mov_b32_e32 v52, v15
	v_mov_b32_e32 v51, v15
	v_mov_b32_e32 v50, v15
	v_mov_b32_e32 v49, v15
	v_mov_b32_e32 v48, v15
	v_mov_b32_e32 v155, v15
	v_mov_b32_e32 v149, 0
	s_waitcnt vmcnt(0) lgkmcnt(0)
	s_barrier
	s_cbranch_scc0 .LBB0_136
	s_and_b64 s[46:47], s[8:9], s[50:51]
	s_andn2_b64 vcc, exec, s[46:47]
	s_mov_b64 s[52:53], -1
	s_cbranch_vccnz .LBB0_143

; #define LAS __attribute__((address_space(3)))
; __device__ __forceinline__ void attn_unit(const bf16_t* __restrict__ Qb, const bf16_t* __restrict__ Kh, const bf16_t* __restrict__ Vh, bf16_t* __restrict__ Ob,
;                                           LAS unsigned char* lds, float MB, int tid, int nrows, int t0, int t1, float* part, float* partl) {
;     ...
;     float l_reg = 0.f; f32x16 o[4] = {}; bf16x8 qr[QREG];
;     LAS unsigned char* qt = lds + LDS_QT + wid * ((12 - QREG) * 1024) + lane * 16;
;     const unsigned qo = (unsigned)((wid * 32 + r32) * LDQ + hi * 8) * 2u;
; #pragma unroll
;     for (int d0 = 0; d0 < QREG; ++d0) qr[d0] = *(const bf16x8*)((const char*)Qb + qo + d0 * 32);
.LBB0_136:
	v_mov_b32_e32 v155, 0
	v_mov_b32_e32 v149, 0
	s_add_i32 s61, s58, 0x4000
	s_add_i32 s62, s58, 0x10000
	s_add_i32 s63, s58, 0x12000
	s_add_i32 s52, s52, 64
	s_mov_b32 s64, 0
	v_mov_b32_e32 v48, 0
	v_mov_b32_e32 v49, v155
	v_mov_b32_e32 v50, v155
	v_mov_b32_e32 v51, v155
	v_mov_b32_e32 v52, v155
	v_mov_b32_e32 v53, v155
	v_mov_b32_e32 v54, v155
	v_mov_b32_e32 v55, v155
	v_mov_b32_e32 v56, v155
	v_mov_b32_e32 v57, v155
	v_mov_b32_e32 v58, v155
	v_mov_b32_e32 v59, v155
	v_mov_b32_e32 v60, v155
	v_mov_b32_e32 v61, v155
	v_mov_b32_e32 v62, v155
	v_mov_b32_e32 v63, v155
	v_mov_b32_e32 v32, 0
	v_mov_b32_e32 v33, v155
	v_mov_b32_e32 v34, v155
	v_mov_b32_e32 v35, v155
	v_mov_b32_e32 v36, v155
	v_mov_b32_e32 v37, v155
	v_mov_b32_e32 v38, v155
	v_mov_b32_e32 v39, v155
	v_mov_b32_e32 v40, v155
	v_mov_b32_e32 v41, v155
	v_mov_b32_e32 v42, v155
	v_mov_b32_e32 v43, v155
	v_mov_b32_e32 v44, v155
	v_mov_b32_e32 v45, v155
	v_mov_b32_e32 v46, v155
	v_mov_b32_e32 v47, v155
	v_mov_b32_e32 v16, 0
	v_mov_b32_e32 v17, v155
	v_mov_b32_e32 v18, v155
	v_mov_b32_e32 v19, v155
	v_mov_b32_e32 v20, v155
	v_mov_b32_e32 v21, v155
	v_mov_b32_e32 v22, v155
	v_mov_b32_e32 v23, v155
	v_mov_b32_e32 v24, v155
	v_mov_b32_e32 v25, v155
	v_mov_b32_e32 v26, v155
	v_mov_b32_e32 v27, v155
	v_mov_b32_e32 v28, v155
	v_mov_b32_e32 v29, v155
	v_mov_b32_e32 v30, v155
	v_mov_b32_e32 v31, v155
	v_mov_b32_e32 v0, 0
	v_mov_b32_e32 v1, v155
	v_mov_b32_e32 v2, v155
	v_mov_b32_e32 v3, v155
	v_mov_b32_e32 v4, v155
	v_mov_b32_e32 v5, v155
	v_mov_b32_e32 v6, v155
	v_mov_b32_e32 v7, v155
	v_mov_b32_e32 v8, v155
	v_mov_b32_e32 v9, v155
	v_mov_b32_e32 v10, v155
	v_mov_b32_e32 v11, v155
	v_mov_b32_e32 v12, v155
	v_mov_b32_e32 v13, v155
	v_mov_b32_e32 v14, v155
	v_mov_b32_e32 v15, v155
	s_branch .LBB0_138

; #define LAS __attribute__((address_space(3)))
; #define SBAR() __builtin_amdgcn_sched_barrier(0)
; __device__ __forceinline__ void qkt(f32x16& p0, f32x16& p1, LAS const unsigned char* Ks, const bf16x8* qr, LAS const unsigned char* qt, int r32, int hi) {
;     p0 = (f32x16){}; p1 = (f32x16){};
; #pragma unroll
;     for (int d0 = 0; d0 < 12; ++d0) { const int cb = (d0 * 16 + hi * 8) * 2;
;         const bf16x8 b0 = *(const LAS bf16x8*)(Ks + KSWZ(r32, cb));
;         const bf16x8 b1 = *(const LAS bf16x8*)(Ks + KSWZ(32 + r32, cb));
;         const bf16x8 qf = d0 < QREG ? qr[d0 < QREG ? d0 : 0] : *(const LAS bf16x8*)(qt + (d0 - QREG) * 1024);
;         p0 = __builtin_amdgcn_mfma_f32_32x32x16_bf16(b0, qf, p0, 0, 0, 0);
;         p1 = __builtin_amdgcn_mfma_f32_32x32x16_bf16(b1, qf, p1, 0, 0, 0);
;         if ((d0 & 3) == 3) SBAR(); }
; }
; __device__ __forceinline__ void expP(f32x16& p0, f32x16& p1, float MB) {
; #pragma unroll
;     for (int r = 0; r < 16; ++r) p0[r] = __builtin_amdgcn_exp2f(p0[r] - MB);
; #pragma unroll
;     for (int r = 0; r < 16; ++r) p1[r] = __builtin_amdgcn_exp2f(p1[r] - MB);
; }
; __device__ __forceinline__ void maskLast(f32x16& p0, f32x16& p1) {
; #pragma unroll
;     for (int r = 8; r < 16; ++r) p0[r] = 0.f;
; #pragma unroll
;     for (int r = 0; r < 16; ++r) p1[r] = 0.f;
; }
; __device__ __forceinline__ void finishP(const f32x16& p0, const f32x16& p1, float& l_reg, bf16x8& pa0, bf16x8& pa1, bf16x8& pa2, bf16x8& pa3) {
;     float ps = 0.f;
; #pragma unroll
;     for (int r = 0; r < 16; ++r) ps += p0[r];
; #pragma unroll
;     for (int r = 0; r < 16; ++r) ps += p1[r];
;     l_reg += ps;
;     ...
;     PK4(p0, 0, pa0); PK4(p0, 8, pa1); PK4(p1, 0, pa2); PK4(p1, 8, pa3);
;     ...
; }
.LBB0_140:
	s_andn2_b64 vcc, exec, s[50:51]
	s_cbranch_vccnz .LBB0_137
	s_mul_i32 s42, s65, 0x6000
	v_add_u32_e32 v213, s42, v209
	v_add_u32_e32 v214, s42, v210
	ds_read_b128 v[216:219], v213 offset:32768
	ds_read_b128 v[224:227], v214 offset:32768
	ds_read_b128 v[240:243], v213 offset:32896
	ds_read_b128 v[244:247], v214 offset:32896
	v_readfirstlane_b32 s70, v206
	s_nop 3
	s_cmpk_eq_i32 s66, 0x80
	s_cselect_b32 s66, 0x7f800000, s70
	s_waitcnt lgkmcnt(3)
	v_mfma_f32_16x16x32_bf16 v[64:67], v[216:219], v[96:99], 0
	v_mfma_f32_16x16x32_bf16 v[72:75], v[216:219], v[120:123], 0
	ds_read_b128 v[216:219], v213 offset:33024
	s_waitcnt lgkmcnt(3)
	v_mfma_f32_16x16x32_bf16 v[64:67], v[224:227], v[100:103], v[64:67]
	v_mfma_f32_16x16x32_bf16 v[72:75], v[224:227], v[124:127], v[72:75]
	ds_read_b128 v[224:227], v214 offset:33024
	s_waitcnt lgkmcnt(3)
	v_mfma_f32_16x16x32_bf16 v[64:67], v[240:243], v[104:107], v[64:67]
	v_mfma_f32_16x16x32_bf16 v[72:75], v[240:243], v[128:131], v[72:75]
	ds_read_b128 v[240:243], v213 offset:38912
	s_waitcnt lgkmcnt(3)
	v_mfma_f32_16x16x32_bf16 v[64:67], v[244:247], v[108:111], v[64:67]
	v_mfma_f32_16x16x32_bf16 v[72:75], v[244:247], v[132:135], v[72:75]
	ds_read_b128 v[244:247], v214 offset:38912
	s_waitcnt lgkmcnt(3)
	v_mfma_f32_16x16x32_bf16 v[64:67], v[216:219], v[112:115], v[64:67]
	v_mfma_f32_16x16x32_bf16 v[72:75], v[216:219], v[136:139], v[72:75]
	ds_read_b128 v[216:219], v213 offset:39040
	s_waitcnt lgkmcnt(3)
	v_mfma_f32_16x16x32_bf16 v[64:67], v[224:227], v[116:119], v[64:67]
	v_mfma_f32_16x16x32_bf16 v[72:75], v[224:227], v[140:143], v[72:75]
	ds_read_b128 v[224:227], v214 offset:39040
	s_waitcnt lgkmcnt(3)
	v_mfma_f32_16x16x32_bf16 v[68:71], v[240:243], v[96:99], 0
	v_mfma_f32_16x16x32_bf16 v[76:79], v[240:243], v[120:123], 0
	ds_read_b128 v[240:243], v213 offset:39168
	s_waitcnt lgkmcnt(3)
	v_mfma_f32_16x16x32_bf16 v[68:71], v[244:247], v[100:103], v[68:71]
	v_mfma_f32_16x16x32_bf16 v[76:79], v[244:247], v[124:127], v[76:79]
	ds_read_b128 v[244:247], v214 offset:39168
	s_waitcnt lgkmcnt(3)
	v_mfma_f32_16x16x32_bf16 v[68:71], v[216:219], v[104:107], v[68:71]
	v_mfma_f32_16x16x32_bf16 v[76:79], v[216:219], v[128:131], v[76:79]
	ds_read_b128 v[216:219], v213 offset:45056
	s_waitcnt lgkmcnt(3)
	v_mfma_f32_16x16x32_bf16 v[68:71], v[224:227], v[108:111], v[68:71]
	v_mfma_f32_16x16x32_bf16 v[76:79], v[224:227], v[132:135], v[76:79]
	ds_read_b128 v[224:227], v214 offset:45056
	s_waitcnt lgkmcnt(3)
	v_mfma_f32_16x16x32_bf16 v[68:71], v[240:243], v[112:115], v[68:71]
	v_mfma_f32_16x16x32_bf16 v[76:79], v[240:243], v[136:139], v[76:79]
	ds_read_b128 v[240:243], v213 offset:45184
	s_waitcnt lgkmcnt(3)
	v_mfma_f32_16x16x32_bf16 v[68:71], v[244:247], v[116:119], v[68:71]
	v_mfma_f32_16x16x32_bf16 v[76:79], v[244:247], v[140:143], v[76:79]
	ds_read_b128 v[244:247], v214 offset:45184
	s_cmp_eq_u32 s66, 0
	s_cbranch_scc1 .Latt_fast
	v_subrev_f32_e32 v64, s70, v64
	v_subrev_f32_e32 v65, s70, v65
	v_exp_f32_e32 v64, v64
	s_waitcnt lgkmcnt(3)
	v_mfma_f32_16x16x32_bf16 v[80:83], v[216:219], v[96:99], 0
	v_subrev_f32_e32 v66, s70, v66
	v_exp_f32_e32 v65, v65
	v_subrev_f32_e32 v67, s70, v67
	v_mfma_f32_16x16x32_bf16 v[88:91], v[216:219], v[120:123], 0
	ds_read_b128 v[216:219], v213 offset:45312
	v_exp_f32_e32 v66, v66
	v_subrev_f32_e32 v68, s66, v68
	v_exp_f32_e32 v67, v67
	s_waitcnt lgkmcnt(3)
	v_mfma_f32_16x16x32_bf16 v[80:83], v[224:227], v[100:103], v[80:83]
	v_add_f32_e32 v146, v64, v65
	v_subrev_f32_e32 v69, s66, v69
	v_exp_f32_e32 v68, v68
	v_mfma_f32_16x16x32_bf16 v[88:91], v[224:227], v[124:127], v[88:91]
	ds_read_b128 v[224:227], v214 offset:45312
	v_add_f32_e32 v146, v66, v146
	v_subrev_f32_e32 v70, s66, v70
	v_exp_f32_e32 v69, v69
	s_waitcnt lgkmcnt(3)
	v_mfma_f32_16x16x32_bf16 v[80:83], v[240:243], v[104:107], v[80:83]
	v_add_f32_e32 v146, v67, v146
	v_subrev_f32_e32 v71, s66, v71
	v_exp_f32_e32 v70, v70
	v_mfma_f32_16x16x32_bf16 v[88:91], v[240:243], v[128:131], v[88:91]
	ds_read_b128 v[240:243], v213 offset:51200
	v_add_f32_e32 v146, v68, v146
	v_exp_f32_e32 v71, v71
	s_waitcnt lgkmcnt(3)
	v_mfma_f32_16x16x32_bf16 v[80:83], v[244:247], v[108:111], v[80:83]
	v_add_f32_e32 v146, v69, v146
	v_add_f32_e32 v146, v70, v146
	v_mfma_f32_16x16x32_bf16 v[88:91], v[244:247], v[132:135], v[88:91]
	ds_read_b128 v[244:247], v214 offset:51200
	v_add_f32_e32 v146, v71, v146
	v_cvt_pk_bf16_f32 v64, v64, v65
	s_waitcnt lgkmcnt(3)
	v_mfma_f32_16x16x32_bf16 v[80:83], v[216:219], v[112:115], v[80:83]
	v_cvt_pk_bf16_f32 v65, v66, v67
	v_cvt_pk_bf16_f32 v66, v68, v69
	v_mfma_f32_16x16x32_bf16 v[88:91], v[216:219], v[136:139], v[88:91]
	ds_read_b128 v[216:219], v213 offset:51328
	v_cvt_pk_bf16_f32 v67, v70, v71
	v_subrev_f32_e32 v72, s70, v72
	ds_read_b128 v[68:71], v214 offset:51328
	s_waitcnt lgkmcnt(4)
	v_mfma_f32_16x16x32_bf16 v[80:83], v[224:227], v[116:119], v[80:83]
	v_subrev_f32_e32 v73, s70, v73
	v_exp_f32_e32 v72, v72
	v_mfma_f32_16x16x32_bf16 v[88:91], v[224:227], v[140:143], v[88:91]
	ds_read_b128 v[224:227], v213 offset:51456
	v_subrev_f32_e32 v74, s70, v74
	v_exp_f32_e32 v73, v73
	s_waitcnt lgkmcnt(4)
	v_mfma_f32_16x16x32_bf16 v[84:87], v[240:243], v[96:99], 0
	v_subrev_f32_e32 v75, s70, v75
	v_exp_f32_e32 v74, v74
	v_mfma_f32_16x16x32_bf16 v[92:95], v[240:243], v[120:123], 0
	ds_read_b128 v[240:243], v214 offset:51456
	v_subrev_f32_e32 v76, s66, v76
	v_exp_f32_e32 v75, v75
	s_waitcnt lgkmcnt(4)
	v_mfma_f32_16x16x32_bf16 v[84:87], v[244:247], v[100:103], v[84:87]
	v_add_f32_e32 v148, v72, v73
	v_subrev_f32_e32 v77, s66, v77
	v_mfma_f32_16x16x32_bf16 v[92:95], v[244:247], v[124:127], v[92:95]
	v_lshl_add_u32 v147, s65, 14, v221
	ds_read_b64_tr_b16 v[244:245], v147 offset:0
	ds_read_b64_tr_b16 v[246:247], v147 offset:4096
	v_exp_f32_e32 v76, v76
	v_add_f32_e32 v148, v74, v148
	s_waitcnt lgkmcnt(5)
; #define SBAR() __builtin_amdgcn_sched_barrier(0)
; template <int D0> __device__ __forceinline__ void pv_load(VBlk& b, int vb) {
;     b.l0 = tr_read<v_rd_off(D0, 0, 0)>(vb); b.h0 = tr_read<v_rd_off(D0, 0, 1)>(vb); b.l1 = tr_read<v_rd_off(D0, 1, 0)>(vb); b.h1 = tr_read<v_rd_off(D0, 1, 1)>(vb);
;     b.l2 = tr_read<v_rd_off(D0, 2, 0)>(vb); b.h2 = tr_read<v_rd_off(D0, 2, 1)>(vb); b.l3 = tr_read<v_rd_off(D0, 3, 0)>(vb); b.h3 = tr_read<v_rd_off(D0, 3, 1)>(vb);
; }
; __device__ __forceinline__ void pv_mma(f32x16& od, const VBlk& b, bf16x8 pa0, bf16x8 pa1, bf16x8 pa2, bf16x8 pa3) {
;     ...
;     od = __builtin_amdgcn_mfma_f32_32x32x16_bf16(pa0, PK(b.l0, b.h0), od, 0, 0, 0);
;     od = __builtin_amdgcn_mfma_f32_32x32x16_bf16(pa1, PK(b.l1, b.h1), od, 0, 0, 0);
;     od = __builtin_amdgcn_mfma_f32_32x32x16_bf16(pa2, PK(b.l2, b.h2), od, 0, 0, 0);
;     od = __builtin_amdgcn_mfma_f32_32x32x16_bf16(pa3, PK(b.l3, b.h3), od, 0, 0, 0);
;     ...
; }
; __device__ __forceinline__ void pv_d0(f32x16* o, int vb, bf16x8 pa0, bf16x8 pa1, bf16x8 pa2, bf16x8 pa3) {
;     VBlk A, B;
;     pv_load<0>(A, vb); pv_load<1>(B, vb);
;     asm volatile("s_waitcnt lgkmcnt(8)" ::: "memory"); SBAR(); pv_mma(o[0], A, pa0, pa1, pa2, pa3); SBAR();
;     pv_load<2>(A, vb);
;     asm volatile("s_waitcnt lgkmcnt(8)" ::: "memory"); SBAR(); pv_mma(o[1], B, pa0, pa1, pa2, pa3); SBAR();
;     pv_load<3>(B, vb);
;     asm volatile("s_waitcnt lgkmcnt(8)" ::: "memory"); SBAR(); pv_mma(o[2], A, pa0, pa1, pa2, pa3); SBAR();
;     asm volatile("s_waitcnt lgkmcnt(0)" ::: "memory"); SBAR(); pv_mma(o[3], B, pa0, pa1, pa2, pa3); SBAR();
; }
; __device__ __forceinline__ void finishP(const f32x16& p0, const f32x16& p1, float& l_reg, bf16x8& pa0, bf16x8& pa1, bf16x8& pa2, bf16x8& pa3) {
;     float ps = 0.f;
; #pragma unroll
;     for (int r = 0; r < 16; ++r) ps += p0[r];
; #pragma unroll
;     for (int r = 0; r < 16; ++r) ps += p1[r];
;     l_reg += ps;
;     ...
;     PK4(p0, 0, pa0); PK4(p0, 8, pa1); PK4(p1, 0, pa2); PK4(p1, 8, pa3);
;     ...
; }
	v_mfma_f32_16x16x32_bf16 v[84:87], v[216:219], v[104:107], v[84:87]
	v_subrev_f32_e32 v78, s66, v78
	v_exp_f32_e32 v77, v77
	v_mfma_f32_16x16x32_bf16 v[92:95], v[216:219], v[128:131], v[92:95]
	ds_read_b64_tr_b16 v[216:217], v147 offset:256
	ds_read_b64_tr_b16 v[218:219], v147 offset:4352
	v_add_f32_e32 v148, v75, v148
	v_subrev_f32_e32 v79, s66, v79
	s_waitcnt lgkmcnt(6)
	v_mfma_f32_16x16x32_bf16 v[84:87], v[68:71], v[108:111], v[84:87]
	v_exp_f32_e32 v78, v78
	v_add_f32_e32 v148, v76, v148
	v_mfma_f32_16x16x32_bf16 v[92:95], v[68:71], v[132:135], v[92:95]
	ds_read_b64_tr_b16 v[68:69], v147 offset:512
	ds_read_b64_tr_b16 v[70:71], v147 offset:4608
	v_exp_f32_e32 v79, v79
	v_add_f32_e32 v148, v77, v148
	s_waitcnt lgkmcnt(7)
	v_mfma_f32_16x16x32_bf16 v[84:87], v[224:227], v[112:115], v[84:87]
	v_add_f32_e32 v148, v78, v148
	v_add_f32_e32 v148, v79, v148
	v_mfma_f32_16x16x32_bf16 v[92:95], v[224:227], v[136:139], v[92:95]
	ds_read_b64_tr_b16 v[224:225], v147 offset:768
	ds_read_b64_tr_b16 v[226:227], v147 offset:4864
	v_cvt_pk_bf16_f32 v72, v72, v73
	v_cvt_pk_bf16_f32 v73, v74, v75
	s_waitcnt lgkmcnt(8)
	v_mfma_f32_16x16x32_bf16 v[84:87], v[240:243], v[116:119], v[84:87]
	v_cvt_pk_bf16_f32 v74, v76, v77
	v_cvt_pk_bf16_f32 v75, v78, v79
	ds_read_b64_tr_b16 v[76:77], v147 offset:1024
	ds_read_b64_tr_b16 v[78:79], v147 offset:5120
	v_mfma_f32_16x16x32_bf16 v[92:95], v[240:243], v[140:143], v[92:95]
	ds_read_b64_tr_b16 v[240:241], v147 offset:1280
	ds_read_b64_tr_b16 v[242:243], v147 offset:5376
	v_subrev_f32_e32 v80, s66, v80
	v_subrev_f32_e32 v81, s66, v81
	v_exp_f32_e32 v80, v80
	v_subrev_f32_e32 v82, s66, v82
	s_waitcnt lgkmcnt(10)
	v_mfma_f32_16x16x32_bf16 v[0:3], v[64:67], v[244:247], v[0:3]
	v_exp_f32_e32 v81, v81
	v_subrev_f32_e32 v83, s66, v83
	v_exp_f32_e32 v82, v82
	v_add_f32_e32 v146, v80, v146
	v_mfma_f32_16x16x32_bf16 v[32:35], v[72:75], v[244:247], v[32:35]
	ds_read_b64_tr_b16 v[244:245], v147 offset:1536
	ds_read_b64_tr_b16 v[246:247], v147 offset:5632
	v_subrev_f32_e32 v84, s66, v84
	v_exp_f32_e32 v83, v83
	v_add_f32_e32 v146, v81, v146
	v_subrev_f32_e32 v85, s66, v85
	s_waitcnt lgkmcnt(10)
	v_mfma_f32_16x16x32_bf16 v[4:7], v[64:67], v[216:219], v[4:7]
	v_exp_f32_e32 v84, v84
	v_add_f32_e32 v146, v82, v146
	v_subrev_f32_e32 v86, s66, v86
	v_exp_f32_e32 v85, v85
	v_mfma_f32_16x16x32_bf16 v[36:39], v[72:75], v[216:219], v[36:39]
	ds_read_b64_tr_b16 v[216:217], v147 offset:1792
	ds_read_b64_tr_b16 v[218:219], v147 offset:5888
	v_add_f32_e32 v146, v83, v146
	v_subrev_f32_e32 v87, s66, v87
	v_exp_f32_e32 v86, v86
	v_add_f32_e32 v146, v84, v146
	s_waitcnt lgkmcnt(10)
	v_mfma_f32_16x16x32_bf16 v[8:11], v[64:67], v[68:71], v[8:11]
	v_exp_f32_e32 v87, v87
	v_add_f32_e32 v146, v85, v146
	v_add_f32_e32 v146, v86, v146
	v_add_f32_e32 v146, v87, v146
	v_mfma_f32_16x16x32_bf16 v[40:43], v[72:75], v[68:71], v[40:43]
	ds_read_b64_tr_b16 v[68:69], v147 offset:8192
	ds_read_b64_tr_b16 v[70:71], v147 offset:12288
	v_cvt_pk_bf16_f32 v80, v80, v81
	v_cvt_pk_bf16_f32 v81, v82, v83
	v_cvt_pk_bf16_f32 v82, v84, v85
	v_cvt_pk_bf16_f32 v83, v86, v87
	s_waitcnt lgkmcnt(10)
	v_mfma_f32_16x16x32_bf16 v[12:15], v[64:67], v[224:227], v[12:15]
	v_add_f32_e32 v155, v155, v146
	v_subrev_f32_e32 v88, s66, v88
	v_subrev_f32_e32 v89, s66, v89
	v_exp_f32_e32 v88, v88
	ds_read_b64_tr_b16 v[84:85], v147 offset:8448
	ds_read_b64_tr_b16 v[86:87], v147 offset:12544
	v_mfma_f32_16x16x32_bf16 v[44:47], v[72:75], v[224:227], v[44:47]
	ds_read_b64_tr_b16 v[224:225], v147 offset:8704
	ds_read_b64_tr_b16 v[226:227], v147 offset:12800
	v_subrev_f32_e32 v90, s66, v90
	v_exp_f32_e32 v89, v89
	v_subrev_f32_e32 v91, s66, v91
	v_exp_f32_e32 v90, v90
	s_waitcnt lgkmcnt(12)
	v_mfma_f32_16x16x32_bf16 v[16:19], v[64:67], v[76:79], v[16:19]
	v_add_f32_e32 v148, v88, v148
	v_subrev_f32_e32 v92, s66, v92
	v_exp_f32_e32 v91, v91
	v_add_f32_e32 v148, v89, v148
	v_mfma_f32_16x16x32_bf16 v[48:51], v[72:75], v[76:79], v[48:51]
	ds_read_b64_tr_b16 v[76:77], v147 offset:8960
	ds_read_b64_tr_b16 v[78:79], v147 offset:13056
	v_subrev_f32_e32 v93, s66, v93
	v_exp_f32_e32 v92, v92
	v_add_f32_e32 v148, v90, v148
	s_waitcnt lgkmcnt(12)
	v_mfma_f32_16x16x32_bf16 v[20:23], v[64:67], v[240:243], v[20:23]
	v_subrev_f32_e32 v94, s66, v94
	v_exp_f32_e32 v93, v93
	v_add_f32_e32 v148, v91, v148
	v_mfma_f32_16x16x32_bf16 v[52:55], v[72:75], v[240:243], v[52:55]
	ds_read_b64_tr_b16 v[240:241], v147 offset:9216
	ds_read_b64_tr_b16 v[242:243], v147 offset:13312
	v_subrev_f32_e32 v95, s66, v95
	v_exp_f32_e32 v94, v94
	v_add_f32_e32 v148, v92, v148
	s_waitcnt lgkmcnt(12)
	v_mfma_f32_16x16x32_bf16 v[24:27], v[64:67], v[244:247], v[24:27]
	v_exp_f32_e32 v95, v95
	v_add_f32_e32 v148, v93, v148
	v_add_f32_e32 v148, v94, v148
	v_mfma_f32_16x16x32_bf16 v[56:59], v[72:75], v[244:247], v[56:59]
	ds_read_b64_tr_b16 v[244:245], v147 offset:9472
	ds_read_b64_tr_b16 v[246:247], v147 offset:13568
	v_add_f32_e32 v148, v95, v148
	v_cvt_pk_bf16_f32 v88, v88, v89
	v_cvt_pk_bf16_f32 v89, v90, v91
	s_waitcnt lgkmcnt(12)
	v_mfma_f32_16x16x32_bf16 v[28:31], v[64:67], v[216:219], v[28:31]
	v_cvt_pk_bf16_f32 v90, v92, v93
	v_cvt_pk_bf16_f32 v91, v94, v95
	v_add_f32_e32 v149, v149, v148
	ds_read_b64_tr_b16 v[92:93], v147 offset:9728
	ds_read_b64_tr_b16 v[94:95], v147 offset:13824
	v_mfma_f32_16x16x32_bf16 v[60:63], v[72:75], v[216:219], v[60:63]
	s_waitcnt lgkmcnt(12)
	v_mfma_f32_16x16x32_bf16 v[0:3], v[80:83], v[68:71], v[0:3]
	v_mfma_f32_16x16x32_bf16 v[32:35], v[88:91], v[68:71], v[32:35]
	ds_read_b64_tr_b16 v[216:217], v147 offset:9984
	ds_read_b64_tr_b16 v[218:219], v147 offset:14080
	s_waitcnt lgkmcnt(12)
	v_mfma_f32_16x16x32_bf16 v[4:7], v[80:83], v[84:87], v[4:7]
	v_mfma_f32_16x16x32_bf16 v[36:39], v[88:91], v[84:87], v[36:39]
	s_waitcnt lgkmcnt(10)
	v_mfma_f32_16x16x32_bf16 v[8:11], v[80:83], v[224:227], v[8:11]
	v_mfma_f32_16x16x32_bf16 v[40:43], v[88:91], v[224:227], v[40:43]
	s_waitcnt lgkmcnt(8)
	v_mfma_f32_16x16x32_bf16 v[12:15], v[80:83], v[76:79], v[12:15]
	v_mfma_f32_16x16x32_bf16 v[44:47], v[88:91], v[76:79], v[44:47]
	s_waitcnt lgkmcnt(6)
	v_mfma_f32_16x16x32_bf16 v[16:19], v[80:83], v[240:243], v[16:19]
	v_mfma_f32_16x16x32_bf16 v[48:51], v[88:91], v[240:243], v[48:51]
	s_waitcnt lgkmcnt(4)
	v_mfma_f32_16x16x32_bf16 v[20:23], v[80:83], v[244:247], v[20:23]
	v_mfma_f32_16x16x32_bf16 v[52:55], v[88:91], v[244:247], v[52:55]
	s_waitcnt lgkmcnt(2)
	v_mfma_f32_16x16x32_bf16 v[24:27], v[80:83], v[92:95], v[24:27]
	v_mfma_f32_16x16x32_bf16 v[56:59], v[88:91], v[92:95], v[56:59]
	s_waitcnt lgkmcnt(0)
	v_mfma_f32_16x16x32_bf16 v[28:31], v[80:83], v[216:219], v[28:31]
	v_mfma_f32_16x16x32_bf16 v[60:63], v[88:91], v[216:219], v[60:63]
	s_branch .LBB0_137
; #define LAS __attribute__((address_space(3)))
; #define SBAR() __builtin_amdgcn_sched_barrier(0)
; __device__ __forceinline__ void qkt(f32x16& p0, f32x16& p1, LAS const unsigned char* Ks, const bf16x8* qr, LAS const unsigned char* qt, int r32, int hi) {
;     p0 = (f32x16){}; p1 = (f32x16){};
; #pragma unroll
;     for (int d0 = 0; d0 < 12; ++d0) { const int cb = (d0 * 16 + hi * 8) * 2;
;         const bf16x8 b0 = *(const LAS bf16x8*)(Ks + KSWZ(r32, cb));
;         const bf16x8 b1 = *(const LAS bf16x8*)(Ks + KSWZ(32 + r32, cb));
;         const bf16x8 qf = d0 < QREG ? qr[d0 < QREG ? d0 : 0] : *(const LAS bf16x8*)(qt + (d0 - QREG) * 1024);
;         p0 = __builtin_amdgcn_mfma_f32_32x32x16_bf16(b0, qf, p0, 0, 0, 0);
;         p1 = __builtin_amdgcn_mfma_f32_32x32x16_bf16(b1, qf, p1, 0, 0, 0);
;         if ((d0 & 3) == 3) SBAR(); }
; }
; __device__ __forceinline__ void expP(f32x16& p0, f32x16& p1, float MB) {
; #pragma unroll
;     for (int r = 0; r < 16; ++r) p0[r] = __builtin_amdgcn_exp2f(p0[r] - MB);
; #pragma unroll
;     for (int r = 0; r < 16; ++r) p1[r] = __builtin_amdgcn_exp2f(p1[r] - MB);
; }
; __device__ __forceinline__ void maskLast(f32x16& p0, f32x16& p1) {
; #pragma unroll
;     for (int r = 8; r < 16; ++r) p0[r] = 0.f;
; #pragma unroll
;     for (int r = 0; r < 16; ++r) p1[r] = 0.f;
; }
; __device__ __forceinline__ void finishP(const f32x16& p0, const f32x16& p1, float& l_reg, bf16x8& pa0, bf16x8& pa1, bf16x8& pa2, bf16x8& pa3) {
;     float ps = 0.f;
; #pragma unroll
;     for (int r = 0; r < 16; ++r) ps += p0[r];
; #pragma unroll
;     for (int r = 0; r < 16; ++r) ps += p1[r];
;     l_reg += ps;
;     ...
;     PK4(p0, 0, pa0); PK4(p0, 8, pa1); PK4(p1, 0, pa2); PK4(p1, 8, pa3);
;     ...
; }
.Latt_fast:
	v_exp_f32_e32 v64, v64
	v_exp_f32_e32 v65, v65
	s_waitcnt lgkmcnt(3)
	v_mfma_f32_16x16x32_bf16 v[80:83], v[216:219], v[96:99], 0
	v_exp_f32_e32 v66, v66
	v_exp_f32_e32 v67, v67
	v_mfma_f32_16x16x32_bf16 v[88:91], v[216:219], v[120:123], 0
	ds_read_b128 v[216:219], v213 offset:45312
	v_add_f32_e32 v146, v64, v65
	v_exp_f32_e32 v68, v68
	s_waitcnt lgkmcnt(3)
	v_mfma_f32_16x16x32_bf16 v[80:83], v[224:227], v[100:103], v[80:83]
	v_add_f32_e32 v146, v66, v146
	v_exp_f32_e32 v69, v69
	v_mfma_f32_16x16x32_bf16 v[88:91], v[224:227], v[124:127], v[88:91]
	ds_read_b128 v[224:227], v214 offset:45312
	v_add_f32_e32 v146, v67, v146
	v_exp_f32_e32 v70, v70
	s_waitcnt lgkmcnt(3)
	v_mfma_f32_16x16x32_bf16 v[80:83], v[240:243], v[104:107], v[80:83]
	v_add_f32_e32 v146, v68, v146
	v_exp_f32_e32 v71, v71
	v_mfma_f32_16x16x32_bf16 v[88:91], v[240:243], v[128:131], v[88:91]
	ds_read_b128 v[240:243], v213 offset:51200
	v_add_f32_e32 v146, v69, v146
	v_add_f32_e32 v146, v70, v146
	s_waitcnt lgkmcnt(3)
	v_mfma_f32_16x16x32_bf16 v[80:83], v[244:247], v[108:111], v[80:83]
	v_add_f32_e32 v146, v71, v146
	v_cvt_pk_bf16_f32 v64, v64, v65
	v_mfma_f32_16x16x32_bf16 v[88:91], v[244:247], v[132:135], v[88:91]
	ds_read_b128 v[244:247], v214 offset:51200
	v_cvt_pk_bf16_f32 v65, v66, v67
	v_cvt_pk_bf16_f32 v66, v68, v69
	s_waitcnt lgkmcnt(3)
	v_mfma_f32_16x16x32_bf16 v[80:83], v[216:219], v[112:115], v[80:83]
	v_cvt_pk_bf16_f32 v67, v70, v71
	v_exp_f32_e32 v72, v72
	ds_read_b128 v[68:71], v213 offset:51328
	v_mfma_f32_16x16x32_bf16 v[88:91], v[216:219], v[136:139], v[88:91]
	ds_read_b128 v[216:219], v214 offset:51328
	v_exp_f32_e32 v73, v73
	v_exp_f32_e32 v74, v74
	s_waitcnt lgkmcnt(4)
	v_mfma_f32_16x16x32_bf16 v[80:83], v[224:227], v[116:119], v[80:83]
	v_exp_f32_e32 v75, v75
	v_add_f32_e32 v148, v72, v73
	v_mfma_f32_16x16x32_bf16 v[88:91], v[224:227], v[140:143], v[88:91]
	ds_read_b128 v[224:227], v213 offset:51456
	v_exp_f32_e32 v76, v76
	v_add_f32_e32 v148, v74, v148
	s_waitcnt lgkmcnt(4)
	v_mfma_f32_16x16x32_bf16 v[84:87], v[240:243], v[96:99], 0
	v_exp_f32_e32 v77, v77
	v_add_f32_e32 v148, v75, v148
	v_mfma_f32_16x16x32_bf16 v[92:95], v[240:243], v[120:123], 0
	ds_read_b128 v[240:243], v214 offset:51456
	v_exp_f32_e32 v78, v78
	s_waitcnt lgkmcnt(4)
	v_mfma_f32_16x16x32_bf16 v[84:87], v[244:247], v[100:103], v[84:87]
	v_add_f32_e32 v148, v76, v148
	v_mfma_f32_16x16x32_bf16 v[92:95], v[244:247], v[124:127], v[92:95]
	v_lshl_add_u32 v147, s65, 14, v221
	ds_read_b64_tr_b16 v[244:245], v147 offset:0
	ds_read_b64_tr_b16 v[246:247], v147 offset:4096
	v_exp_f32_e32 v79, v79
	s_waitcnt lgkmcnt(5)
	v_mfma_f32_16x16x32_bf16 v[84:87], v[68:71], v[104:107], v[84:87]
	v_add_f32_e32 v148, v77, v148
	v_mfma_f32_16x16x32_bf16 v[92:95], v[68:71], v[128:131], v[92:95]
	ds_read_b64_tr_b16 v[68:69], v147 offset:256
	ds_read_b64_tr_b16 v[70:71], v147 offset:4352
	v_add_f32_e32 v148, v78, v148
	s_waitcnt lgkmcnt(6)
	v_mfma_f32_16x16x32_bf16 v[84:87], v[216:219], v[108:111], v[84:87]
	v_add_f32_e32 v148, v79, v148
	v_mfma_f32_16x16x32_bf16 v[92:95], v[216:219], v[132:135], v[92:95]
	ds_read_b64_tr_b16 v[216:217], v147 offset:512
	ds_read_b64_tr_b16 v[218:219], v147 offset:4608
	v_cvt_pk_bf16_f32 v72, v72, v73
	s_waitcnt lgkmcnt(7)
	v_mfma_f32_16x16x32_bf16 v[84:87], v[224:227], v[112:115], v[84:87]
	v_cvt_pk_bf16_f32 v73, v74, v75
	v_mfma_f32_16x16x32_bf16 v[92:95], v[224:227], v[136:139], v[92:95]
	ds_read_b64_tr_b16 v[224:225], v147 offset:768
	ds_read_b64_tr_b16 v[226:227], v147 offset:4864
	v_cvt_pk_bf16_f32 v74, v76, v77
	s_waitcnt lgkmcnt(8)
	v_mfma_f32_16x16x32_bf16 v[84:87], v[240:243], v[116:119], v[84:87]
	v_cvt_pk_bf16_f32 v75, v78, v79
	ds_read_b64_tr_b16 v[76:77], v147 offset:1024
	ds_read_b64_tr_b16 v[78:79], v147 offset:5120
	v_mfma_f32_16x16x32_bf16 v[92:95], v[240:243], v[140:143], v[92:95]
	ds_read_b64_tr_b16 v[240:241], v147 offset:1280
	ds_read_b64_tr_b16 v[242:243], v147 offset:5376
	v_exp_f32_e32 v80, v80
	v_exp_f32_e32 v81, v81
	v_exp_f32_e32 v82, v82
	s_waitcnt lgkmcnt(10)
	v_mfma_f32_16x16x32_bf16 v[0:3], v[64:67], v[244:247], v[0:3]
	v_add_f32_e32 v146, v80, v146
	v_exp_f32_e32 v83, v83
	v_add_f32_e32 v146, v81, v146
	v_mfma_f32_16x16x32_bf16 v[32:35], v[72:75], v[244:247], v[32:35]
	ds_read_b64_tr_b16 v[244:245], v147 offset:1536
	ds_read_b64_tr_b16 v[246:247], v147 offset:5632
	v_exp_f32_e32 v84, v84
	v_add_f32_e32 v146, v82, v146
	v_exp_f32_e32 v85, v85
	s_waitcnt lgkmcnt(10)
; #define SBAR() __builtin_amdgcn_sched_barrier(0)
; template <int D0> __device__ __forceinline__ void pv_load(VBlk& b, int vb) {
;     b.l0 = tr_read<v_rd_off(D0, 0, 0)>(vb); b.h0 = tr_read<v_rd_off(D0, 0, 1)>(vb); b.l1 = tr_read<v_rd_off(D0, 1, 0)>(vb); b.h1 = tr_read<v_rd_off(D0, 1, 1)>(vb);
;     b.l2 = tr_read<v_rd_off(D0, 2, 0)>(vb); b.h2 = tr_read<v_rd_off(D0, 2, 1)>(vb); b.l3 = tr_read<v_rd_off(D0, 3, 0)>(vb); b.h3 = tr_read<v_rd_off(D0, 3, 1)>(vb);
; }
; __device__ __forceinline__ void pv_mma(f32x16& od, const VBlk& b, bf16x8 pa0, bf16x8 pa1, bf16x8 pa2, bf16x8 pa3) {
;     ...
;     od = __builtin_amdgcn_mfma_f32_32x32x16_bf16(pa0, PK(b.l0, b.h0), od, 0, 0, 0);
;     od = __builtin_amdgcn_mfma_f32_32x32x16_bf16(pa1, PK(b.l1, b.h1), od, 0, 0, 0);
;     od = __builtin_amdgcn_mfma_f32_32x32x16_bf16(pa2, PK(b.l2, b.h2), od, 0, 0, 0);
;     od = __builtin_amdgcn_mfma_f32_32x32x16_bf16(pa3, PK(b.l3, b.h3), od, 0, 0, 0);
;     ...
; }
; __device__ __forceinline__ void pv_d0(f32x16* o, int vb, bf16x8 pa0, bf16x8 pa1, bf16x8 pa2, bf16x8 pa3) {
;     VBlk A, B;
;     pv_load<0>(A, vb); pv_load<1>(B, vb);
;     asm volatile("s_waitcnt lgkmcnt(8)" ::: "memory"); SBAR(); pv_mma(o[0], A, pa0, pa1, pa2, pa3); SBAR();
;     pv_load<2>(A, vb);
;     asm volatile("s_waitcnt lgkmcnt(8)" ::: "memory"); SBAR(); pv_mma(o[1], B, pa0, pa1, pa2, pa3); SBAR();
;     pv_load<3>(B, vb);
;     asm volatile("s_waitcnt lgkmcnt(8)" ::: "memory"); SBAR(); pv_mma(o[2], A, pa0, pa1, pa2, pa3); SBAR();
;     asm volatile("s_waitcnt lgkmcnt(0)" ::: "memory"); SBAR(); pv_mma(o[3], B, pa0, pa1, pa2, pa3); SBAR();
; }
; __device__ __forceinline__ void finishP(const f32x16& p0, const f32x16& p1, float& l_reg, bf16x8& pa0, bf16x8& pa1, bf16x8& pa2, bf16x8& pa3) {
;     float ps = 0.f;
; #pragma unroll
;     for (int r = 0; r < 16; ++r) ps += p0[r];
; #pragma unroll
;     for (int r = 0; r < 16; ++r) ps += p1[r];
;     l_reg += ps;
;     ...
;     PK4(p0, 0, pa0); PK4(p0, 8, pa1); PK4(p1, 0, pa2); PK4(p1, 8, pa3);
;     ...
; }
	v_mfma_f32_16x16x32_bf16 v[4:7], v[64:67], v[68:71], v[4:7]
	v_add_f32_e32 v146, v83, v146
	v_exp_f32_e32 v86, v86
	v_add_f32_e32 v146, v84, v146
	v_mfma_f32_16x16x32_bf16 v[36:39], v[72:75], v[68:71], v[36:39]
	ds_read_b64_tr_b16 v[68:69], v147 offset:1792
	ds_read_b64_tr_b16 v[70:71], v147 offset:5888
	v_exp_f32_e32 v87, v87
	v_add_f32_e32 v146, v85, v146
	v_add_f32_e32 v146, v86, v146
	s_waitcnt lgkmcnt(10)
	v_mfma_f32_16x16x32_bf16 v[8:11], v[64:67], v[216:219], v[8:11]
	v_add_f32_e32 v146, v87, v146
	v_cvt_pk_bf16_f32 v80, v80, v81
	v_cvt_pk_bf16_f32 v81, v82, v83
	v_mfma_f32_16x16x32_bf16 v[40:43], v[72:75], v[216:219], v[40:43]
	ds_read_b64_tr_b16 v[216:217], v147 offset:8192
	ds_read_b64_tr_b16 v[218:219], v147 offset:12288
	v_cvt_pk_bf16_f32 v82, v84, v85
	v_cvt_pk_bf16_f32 v83, v86, v87
	v_add_f32_e32 v155, v155, v146
	ds_read_b64_tr_b16 v[84:85], v147 offset:8448
	ds_read_b64_tr_b16 v[86:87], v147 offset:12544
	s_waitcnt lgkmcnt(12)
	v_mfma_f32_16x16x32_bf16 v[12:15], v[64:67], v[224:227], v[12:15]
	v_exp_f32_e32 v88, v88
	v_exp_f32_e32 v89, v89
	v_exp_f32_e32 v90, v90
	v_mfma_f32_16x16x32_bf16 v[44:47], v[72:75], v[224:227], v[44:47]
	ds_read_b64_tr_b16 v[224:225], v147 offset:8704
	ds_read_b64_tr_b16 v[226:227], v147 offset:12800
	v_add_f32_e32 v148, v88, v148
	v_exp_f32_e32 v91, v91
	v_add_f32_e32 v148, v89, v148
	s_waitcnt lgkmcnt(12)
	v_mfma_f32_16x16x32_bf16 v[16:19], v[64:67], v[76:79], v[16:19]
	v_exp_f32_e32 v92, v92
	v_add_f32_e32 v148, v90, v148
	v_exp_f32_e32 v93, v93
	v_mfma_f32_16x16x32_bf16 v[48:51], v[72:75], v[76:79], v[48:51]
	ds_read_b64_tr_b16 v[76:77], v147 offset:8960
	ds_read_b64_tr_b16 v[78:79], v147 offset:13056
	v_add_f32_e32 v148, v91, v148
	v_exp_f32_e32 v94, v94
	s_waitcnt lgkmcnt(12)
	v_mfma_f32_16x16x32_bf16 v[20:23], v[64:67], v[240:243], v[20:23]
	v_add_f32_e32 v148, v92, v148
	v_exp_f32_e32 v95, v95
	v_mfma_f32_16x16x32_bf16 v[52:55], v[72:75], v[240:243], v[52:55]
	ds_read_b64_tr_b16 v[240:241], v147 offset:9216
	ds_read_b64_tr_b16 v[242:243], v147 offset:13312
	v_add_f32_e32 v148, v93, v148
	v_add_f32_e32 v148, v94, v148
	s_waitcnt lgkmcnt(12)
	v_mfma_f32_16x16x32_bf16 v[24:27], v[64:67], v[244:247], v[24:27]
	v_add_f32_e32 v148, v95, v148
	v_cvt_pk_bf16_f32 v88, v88, v89
	v_mfma_f32_16x16x32_bf16 v[56:59], v[72:75], v[244:247], v[56:59]
	ds_read_b64_tr_b16 v[244:245], v147 offset:9472
	ds_read_b64_tr_b16 v[246:247], v147 offset:13568
	v_cvt_pk_bf16_f32 v89, v90, v91
	v_cvt_pk_bf16_f32 v90, v92, v93
	s_waitcnt lgkmcnt(12)
	v_mfma_f32_16x16x32_bf16 v[28:31], v[64:67], v[68:71], v[28:31]
	v_cvt_pk_bf16_f32 v91, v94, v95
	v_add_f32_e32 v149, v149, v148
	ds_read_b64_tr_b16 v[92:93], v147 offset:9728
	ds_read_b64_tr_b16 v[94:95], v147 offset:13824
	v_mfma_f32_16x16x32_bf16 v[60:63], v[72:75], v[68:71], v[60:63]
	s_waitcnt lgkmcnt(12)
	v_mfma_f32_16x16x32_bf16 v[0:3], v[80:83], v[216:219], v[0:3]
	v_mfma_f32_16x16x32_bf16 v[32:35], v[88:91], v[216:219], v[32:35]
	ds_read_b64_tr_b16 v[68:69], v147 offset:9984
	ds_read_b64_tr_b16 v[70:71], v147 offset:14080
	s_waitcnt lgkmcnt(12)
	v_mfma_f32_16x16x32_bf16 v[4:7], v[80:83], v[84:87], v[4:7]
	v_mfma_f32_16x16x32_bf16 v[36:39], v[88:91], v[84:87], v[36:39]
	s_waitcnt lgkmcnt(10)
	v_mfma_f32_16x16x32_bf16 v[8:11], v[80:83], v[224:227], v[8:11]
	v_mfma_f32_16x16x32_bf16 v[40:43], v[88:91], v[224:227], v[40:43]
	s_waitcnt lgkmcnt(8)
	v_mfma_f32_16x16x32_bf16 v[12:15], v[80:83], v[76:79], v[12:15]
	v_mfma_f32_16x16x32_bf16 v[44:47], v[88:91], v[76:79], v[44:47]
	s_waitcnt lgkmcnt(6)
	v_mfma_f32_16x16x32_bf16 v[16:19], v[80:83], v[240:243], v[16:19]
	v_mfma_f32_16x16x32_bf16 v[48:51], v[88:91], v[240:243], v[48:51]
	s_waitcnt lgkmcnt(4)
	v_mfma_f32_16x16x32_bf16 v[20:23], v[80:83], v[244:247], v[20:23]
	v_mfma_f32_16x16x32_bf16 v[52:55], v[88:91], v[244:247], v[52:55]
	s_waitcnt lgkmcnt(2)
	v_mfma_f32_16x16x32_bf16 v[24:27], v[80:83], v[92:95], v[24:27]
	v_mfma_f32_16x16x32_bf16 v[56:59], v[88:91], v[92:95], v[56:59]
	s_waitcnt lgkmcnt(0)
	v_mfma_f32_16x16x32_bf16 v[28:31], v[80:83], v[68:71], v[28:31]
	v_mfma_f32_16x16x32_bf16 v[60:63], v[88:91], v[68:71], v[60:63]
	s_branch .LBB0_137

; __device__ __forceinline__ bf16_t to_bf1(float f) { return (bf16_t)(cvt_pk_bf16(f, 0.f) & 0xffffu); }
; __device__ __forceinline__ float shx(float v, int o, int lane) { return __int_as_float(__builtin_amdgcn_ds_bpermute((lane ^ o) << 2, __float_as_int(v))); }
; __device__ __forceinline__ int crow(int r, int hi) { return (r & 3) + 8 * (r >> 2) + 4 * hi; }
; __device__ __forceinline__ void attn_unit(const bf16_t* __restrict__ Qb, const bf16_t* __restrict__ Kh, const bf16_t* __restrict__ Vh, bf16_t* __restrict__ Ob,
;                                           LAS unsigned char* lds, float MB, int tid, int nrows, int t0, int t1, float* part, float* partl) {
;     ...
;     } else if (act) {
;     l_reg += shx(l_reg, 32, lane);
;     if (hi == 0) li_l[r32] = l_reg;
;     asm volatile("s_waitcnt lgkmcnt(0)" ::: "memory");
;     float rli[16];
; #pragma unroll
;     for (int r = 0; r < 16; ++r) rli[r] = __builtin_amdgcn_rcpf(li_l[crow(r, hi)]);
;     int r32e = r32; asm volatile("" : "+v"(r32e));
;     const unsigned ob = (unsigned)((wid * 32) * LDO + r32e) * 2u;
; #pragma unroll
;     for (int r = 0; r < 16; ++r) { const int orow = crow(r, hi);
;         if (wid * 32 + orow < nrows) {
; #pragma unroll
;         for (int d0 = 0; d0 < 4; ++d0) *(bf16_t*)((char*)Ob + ob + (unsigned)(orow * LDO + d0 * 32) * 2u) = to_bf1(o[d0][r] * rli[r]); } }
.LBB0_143:
	s_andn2_b64 vcc, exec, s[50:51]
	s_cbranch_vccnz .LBB0_179
	ds_bpermute_b32 v64, v222, v155
	ds_bpermute_b32 v65, v222, v149
	s_and_b32 s37, s37, 0x3fffffc0
	s_lshl_b32 s37, s37, 2
	s_add_i32 s37, s37, 0x14000
	v_xor_b32_e32 v66, 0xc0, v222
	s_waitcnt lgkmcnt(0)
	v_add_f32_e32 v64, v155, v64
	v_add_f32_e32 v65, v149, v65
	s_nop 0
	ds_bpermute_b32 v67, v66, v64
	ds_bpermute_b32 v68, v66, v65
	s_waitcnt lgkmcnt(0)
	v_add_f32_e32 v64, v64, v67
	v_add_f32_e32 v65, v65, v68
	s_and_saveexec_b64 s[50:51], s[0:1]
	v_lshl_add_u32 v66, v151, 2, s37
	ds_write_b32 v66, v64
	ds_write_b32 v66, v65 offset:64
	s_or_b64 exec, exec, s[50:51]
	s_waitcnt lgkmcnt(0)
	v_and_b32_e32 v66, 0x30, v150
	v_add_u32_e32 v66, s37, v66
	ds_read_b128 v[68:71], v66
	ds_read_b128 v[72:75], v66 offset:64
	s_lshl_b64 s[46:47], s[48:49], 12
	s_add_u32 s42, s82, s46
	s_addc_u32 s43, s83, s47
	s_lshl_b32 s46, s29, 7
	s_ashr_i32 s47, s46, 31
	s_lshl_b64 s[46:47], s[46:47], 1
	s_add_u32 s46, s42, s46
	s_addc_u32 s47, s43, s47
	s_lshl_b32 s29, s33, 17
	v_and_b32_e32 v76, 15, v150
	v_bfe_u32 v77, v150, 4, 2
	v_lshl_add_u32 v76, v76, 1, s29
	v_lshl_add_u32 v144, v77, 14, v76
	v_lshl_add_u64 v[80:81], s[46:47], 0, v[144:145]
	s_mov_b64 s[42:43], 0x1000
	s_waitcnt lgkmcnt(0)
	v_rcp_f32_e32 v68, v68
	v_rcp_f32_e32 v69, v69
	v_rcp_f32_e32 v70, v70
	v_rcp_f32_e32 v71, v71
	v_rcp_f32_e32 v72, v72
	v_rcp_f32_e32 v73, v73
	v_rcp_f32_e32 v74, v74
	v_rcp_f32_e32 v75, v75
	s_nop 0
	v_mul_f32_e32 v82, v0, v68
	v_cvt_pk_bf16_f32 v82, v82, v145
	flat_store_short v[80:81], v82
	v_mul_f32_e32 v83, v4, v68
	v_cvt_pk_bf16_f32 v83, v83, v145
	flat_store_short v[80:81], v83 offset:32
	v_mul_f32_e32 v84, v8, v68
	v_cvt_pk_bf16_f32 v84, v84, v145
	flat_store_short v[80:81], v84 offset:64
	v_mul_f32_e32 v85, v12, v68
	v_cvt_pk_bf16_f32 v85, v85, v145
	flat_store_short v[80:81], v85 offset:96
	v_mul_f32_e32 v86, v16, v68
	v_cvt_pk_bf16_f32 v86, v86, v145
	flat_store_short v[80:81], v86 offset:128
	v_mul_f32_e32 v87, v20, v68
	v_cvt_pk_bf16_f32 v87, v87, v145
	flat_store_short v[80:81], v87 offset:160
	v_mul_f32_e32 v88, v24, v68
	v_cvt_pk_bf16_f32 v88, v88, v145
	flat_store_short v[80:81], v88 offset:192
	v_mul_f32_e32 v89, v28, v68
	v_cvt_pk_bf16_f32 v89, v89, v145
	flat_store_short v[80:81], v89 offset:224
	v_lshl_add_u64 v[80:81], v[80:81], 0, s[42:43]
	v_mul_f32_e32 v82, v1, v69
	v_cvt_pk_bf16_f32 v82, v82, v145
	flat_store_short v[80:81], v82
	v_mul_f32_e32 v83, v5, v69
	v_cvt_pk_bf16_f32 v83, v83, v145
	flat_store_short v[80:81], v83 offset:32
	v_mul_f32_e32 v84, v9, v69
	v_cvt_pk_bf16_f32 v84, v84, v145
	flat_store_short v[80:81], v84 offset:64
	v_mul_f32_e32 v85, v13, v69
	v_cvt_pk_bf16_f32 v85, v85, v145
	flat_store_short v[80:81], v85 offset:96
	v_mul_f32_e32 v86, v17, v69
	v_cvt_pk_bf16_f32 v86, v86, v145
	flat_store_short v[80:81], v86 offset:128
	v_mul_f32_e32 v87, v21, v69
	v_cvt_pk_bf16_f32 v87, v87, v145
	flat_store_short v[80:81], v87 offset:160
	v_mul_f32_e32 v88, v25, v69
	v_cvt_pk_bf16_f32 v88, v88, v145
	flat_store_short v[80:81], v88 offset:192
	v_mul_f32_e32 v89, v29, v69
	v_cvt_pk_bf16_f32 v89, v89, v145
	flat_store_short v[80:81], v89 offset:224
	v_lshl_add_u64 v[80:81], v[80:81], 0, s[42:43]
	v_mul_f32_e32 v82, v2, v70
	v_cvt_pk_bf16_f32 v82, v82, v145
	flat_store_short v[80:81], v82
	v_mul_f32_e32 v83, v6, v70
	v_cvt_pk_bf16_f32 v83, v83, v145
	flat_store_short v[80:81], v83 offset:32
	v_mul_f32_e32 v84, v10, v70
	v_cvt_pk_bf16_f32 v84, v84, v145
	flat_store_short v[80:81], v84 offset:64
	v_mul_f32_e32 v85, v14, v70
	v_cvt_pk_bf16_f32 v85, v85, v145
	flat_store_short v[80:81], v85 offset:96
	v_mul_f32_e32 v86, v18, v70
	v_cvt_pk_bf16_f32 v86, v86, v145
	flat_store_short v[80:81], v86 offset:128
	v_mul_f32_e32 v87, v22, v70
	v_cvt_pk_bf16_f32 v87, v87, v145
	flat_store_short v[80:81], v87 offset:160
	v_mul_f32_e32 v88, v26, v70
	v_cvt_pk_bf16_f32 v88, v88, v145
	flat_store_short v[80:81], v88 offset:192
	v_mul_f32_e32 v89, v30, v70
	v_cvt_pk_bf16_f32 v89, v89, v145
	flat_store_short v[80:81], v89 offset:224
	v_lshl_add_u64 v[80:81], v[80:81], 0, s[42:43]
	v_mul_f32_e32 v82, v3, v71
	v_cvt_pk_bf16_f32 v82, v82, v145
	flat_store_short v[80:81], v82
	v_mul_f32_e32 v83, v7, v71
	v_cvt_pk_bf16_f32 v83, v83, v145
; __device__ __forceinline__ bf16_t to_bf1(float f) { return (bf16_t)(cvt_pk_bf16(f, 0.f) & 0xffffu); }
; __device__ __forceinline__ int crow(int r, int hi) { return (r & 3) + 8 * (r >> 2) + 4 * hi; }
; __device__ __forceinline__ void attn_unit(const bf16_t* __restrict__ Qb, const bf16_t* __restrict__ Kh, const bf16_t* __restrict__ Vh, bf16_t* __restrict__ Ob,
;                                           LAS unsigned char* lds, float MB, int tid, int nrows, int t0, int t1, float* part, float* partl) {
;     ...
; #pragma unroll
;     for (int r = 0; r < 16; ++r) { const int orow = crow(r, hi);
;         if (wid * 32 + orow < nrows) {
; #pragma unroll
;         for (int d0 = 0; d0 < 4; ++d0) *(bf16_t*)((char*)Ob + ob + (unsigned)(orow * LDO + d0 * 32) * 2u) = to_bf1(o[d0][r] * rli[r]); } }
;     }
	flat_store_short v[80:81], v83 offset:32
	v_mul_f32_e32 v84, v11, v71
	v_cvt_pk_bf16_f32 v84, v84, v145
	flat_store_short v[80:81], v84 offset:64
	v_mul_f32_e32 v85, v15, v71
	v_cvt_pk_bf16_f32 v85, v85, v145
	flat_store_short v[80:81], v85 offset:96
	v_mul_f32_e32 v86, v19, v71
	v_cvt_pk_bf16_f32 v86, v86, v145
	flat_store_short v[80:81], v86 offset:128
	v_mul_f32_e32 v87, v23, v71
	v_cvt_pk_bf16_f32 v87, v87, v145
	flat_store_short v[80:81], v87 offset:160
	v_mul_f32_e32 v88, v27, v71
	v_cvt_pk_bf16_f32 v88, v88, v145
	flat_store_short v[80:81], v88 offset:192
	v_mul_f32_e32 v89, v31, v71
	v_cvt_pk_bf16_f32 v89, v89, v145
	flat_store_short v[80:81], v89 offset:224
	s_mov_b64 s[42:43], 0xd000
	v_lshl_add_u64 v[80:81], v[80:81], 0, s[42:43]
	s_mov_b64 s[42:43], 0x1000
	v_mul_f32_e32 v82, v32, v72
	v_cvt_pk_bf16_f32 v82, v82, v145
	flat_store_short v[80:81], v82
	v_mul_f32_e32 v83, v36, v72
	v_cvt_pk_bf16_f32 v83, v83, v145
	flat_store_short v[80:81], v83 offset:32
	v_mul_f32_e32 v84, v40, v72
	v_cvt_pk_bf16_f32 v84, v84, v145
	flat_store_short v[80:81], v84 offset:64
	v_mul_f32_e32 v85, v44, v72
	v_cvt_pk_bf16_f32 v85, v85, v145
	flat_store_short v[80:81], v85 offset:96
	v_mul_f32_e32 v86, v48, v72
	v_cvt_pk_bf16_f32 v86, v86, v145
	flat_store_short v[80:81], v86 offset:128
	v_mul_f32_e32 v87, v52, v72
	v_cvt_pk_bf16_f32 v87, v87, v145
	flat_store_short v[80:81], v87 offset:160
	v_mul_f32_e32 v88, v56, v72
	v_cvt_pk_bf16_f32 v88, v88, v145
	flat_store_short v[80:81], v88 offset:192
	v_mul_f32_e32 v89, v60, v72
	v_cvt_pk_bf16_f32 v89, v89, v145
	flat_store_short v[80:81], v89 offset:224
	v_lshl_add_u64 v[80:81], v[80:81], 0, s[42:43]
	v_mul_f32_e32 v82, v33, v73
	v_cvt_pk_bf16_f32 v82, v82, v145
	flat_store_short v[80:81], v82
	v_mul_f32_e32 v83, v37, v73
	v_cvt_pk_bf16_f32 v83, v83, v145
	flat_store_short v[80:81], v83 offset:32
	v_mul_f32_e32 v84, v41, v73
	v_cvt_pk_bf16_f32 v84, v84, v145
	flat_store_short v[80:81], v84 offset:64
	v_mul_f32_e32 v85, v45, v73
	v_cvt_pk_bf16_f32 v85, v85, v145
	flat_store_short v[80:81], v85 offset:96
	v_mul_f32_e32 v86, v49, v73
	v_cvt_pk_bf16_f32 v86, v86, v145
	flat_store_short v[80:81], v86 offset:128
	v_mul_f32_e32 v87, v53, v73
	v_cvt_pk_bf16_f32 v87, v87, v145
	flat_store_short v[80:81], v87 offset:160
	v_mul_f32_e32 v88, v57, v73
	v_cvt_pk_bf16_f32 v88, v88, v145
	flat_store_short v[80:81], v88 offset:192
	v_mul_f32_e32 v89, v61, v73
	v_cvt_pk_bf16_f32 v89, v89, v145
	flat_store_short v[80:81], v89 offset:224
	v_lshl_add_u64 v[80:81], v[80:81], 0, s[42:43]
	v_mul_f32_e32 v82, v34, v74
	v_cvt_pk_bf16_f32 v82, v82, v145
	flat_store_short v[80:81], v82
	v_mul_f32_e32 v83, v38, v74
	v_cvt_pk_bf16_f32 v83, v83, v145
	flat_store_short v[80:81], v83 offset:32
	v_mul_f32_e32 v84, v42, v74
	v_cvt_pk_bf16_f32 v84, v84, v145
	flat_store_short v[80:81], v84 offset:64
	v_mul_f32_e32 v85, v46, v74
	v_cvt_pk_bf16_f32 v85, v85, v145
	flat_store_short v[80:81], v85 offset:96
	v_mul_f32_e32 v86, v50, v74
	v_cvt_pk_bf16_f32 v86, v86, v145
	flat_store_short v[80:81], v86 offset:128
	v_mul_f32_e32 v87, v54, v74
	v_cvt_pk_bf16_f32 v87, v87, v145
	flat_store_short v[80:81], v87 offset:160
	v_mul_f32_e32 v88, v58, v74
	v_cvt_pk_bf16_f32 v88, v88, v145
	flat_store_short v[80:81], v88 offset:192
	v_mul_f32_e32 v89, v62, v74
	v_cvt_pk_bf16_f32 v89, v89, v145
	flat_store_short v[80:81], v89 offset:224
	v_lshl_add_u64 v[80:81], v[80:81], 0, s[42:43]
	v_mul_f32_e32 v82, v35, v75
	v_cvt_pk_bf16_f32 v82, v82, v145
	flat_store_short v[80:81], v82
	v_mul_f32_e32 v83, v39, v75
	v_cvt_pk_bf16_f32 v83, v83, v145
	flat_store_short v[80:81], v83 offset:32
	v_mul_f32_e32 v84, v43, v75
	v_cvt_pk_bf16_f32 v84, v84, v145
	flat_store_short v[80:81], v84 offset:64
	v_mul_f32_e32 v85, v47, v75
	v_cvt_pk_bf16_f32 v85, v85, v145
	flat_store_short v[80:81], v85 offset:96
	v_mul_f32_e32 v86, v51, v75
	v_cvt_pk_bf16_f32 v86, v86, v145
	flat_store_short v[80:81], v86 offset:128
	v_mul_f32_e32 v87, v55, v75
	v_cvt_pk_bf16_f32 v87, v87, v145
	flat_store_short v[80:81], v87 offset:160
	v_mul_f32_e32 v88, v59, v75
	v_cvt_pk_bf16_f32 v88, v88, v145
	flat_store_short v[80:81], v88 offset:192
	v_mul_f32_e32 v89, v63, v75
	v_cvt_pk_bf16_f32 v89, v89, v145
	flat_store_short v[80:81], v89 offset:224

; __device__ __forceinline__ float shx(float v, int o, int lane) { return __int_as_float(__builtin_amdgcn_ds_bpermute((lane ^ o) << 2, __float_as_int(v))); }
; __device__ __forceinline__ void attn_unit(const bf16_t* __restrict__ Qb, const bf16_t* __restrict__ Kh, const bf16_t* __restrict__ Vh, bf16_t* __restrict__ Ob,
;                                           LAS unsigned char* lds, float MB, int tid, int nrows, int t0, int t1, float* part, float* partl) {
;     ...
;     if (act && part) {
;         l_reg += shx(l_reg, 32, lane);
;         if (hi == 0 && r32 < 16) partl[r32] = l_reg;
.LBB0_180:
	ds_bpermute_b32 v40, v222, v155
	s_ashr_i32 s37, s36, 31
	v_xor_b32_e32 v43, 0xc0, v222
	s_waitcnt lgkmcnt(0)
	v_add_f32_e32 v42, v155, v40
	s_nop 0
	ds_bpermute_b32 v40, v43, v42
	s_waitcnt lgkmcnt(0)
	v_add_f32_e32 v42, v42, v40
	s_and_saveexec_b64 s[48:49], s[0:1]
	s_cbranch_execz .LBB0_127
	s_lshl_b64 s[28:29], s[36:37], 6
	v_lshl_add_u64 v[40:41], v[198:199], 0, s[28:29]
	flat_store_dword v[40:41], v42
	s_branch .LBB0_127
